# K-loop: loop counter update and exit compare moved ahead of the block-closing barrier (only the branch follows it)
# speedup vs baseline: 1.0017x; 1.0017x over previous
; #define PG8_STAGE(bufoff, gbase, voff) do { _Pragma("unroll") for (int _i = 0; _i < 2; ++_i) \
;         __builtin_amdgcn_global_load_lds((const unsigned*)((const char*)(gbase) + (voff)[_i]), (PG8_LAS unsigned*)(lds + (bufoff) + ldsw + _i * 8192), 16, 0, 0); } while (0)
; #define PG8_LDA(dst, b, h) do { _Pragma("unroll") for (int m = 0; m < 4; ++m) _Pragma("unroll") for (int k = 0; k < 2; ++k) dst[m][k] = *(const PG8_LAS bf16x8*)(lds + PG8_SA(b, h) + aoff + m * 2048 + k * 1024); } while (0)
; #define PG8_MMA(ai, bj, At, Bt) do { __builtin_amdgcn_s_setprio(1); _Pragma("unroll") for (int m = 0; m < 4; ++m) _Pragma("unroll") for (int n = 0; n < 2; ++n) _Pragma("unroll") for (int k = 0; k < 2; ++k) \
;         acc[ai][bj][m][n] = __builtin_amdgcn_mfma_f32_16x16x32_bf16(Bt[n][k], At[m][k], acc[ai][bj][m][n], 0, 0, 0); __builtin_amdgcn_s_setprio(0); } while (0)
; #define PG8_WAIT_V(n) asm volatile("s_waitcnt vmcnt(" #n ")" ::: "memory")
; #define PG8_WAIT_L(n) asm volatile("s_waitcnt lgkmcnt(" #n ")" ::: "memory")
; #define PG8_BAR __builtin_amdgcn_s_barrier()
; #define PG8_SCHED __builtin_amdgcn_sched_barrier(0)
; template <class Epi, class Sched, bool ALIGN_EPI = false, bool SP2 = false>
; __device__ __forceinline__ void gemm_phase(PG8_LAS unsigned char* lds, const Gemm g, const Sched& S, const Epi& E, const int wave_id) {
;     ...
;             PG8_WAIT_V(8); PG8_WAIT_L(0); PG8_BAR; PG8_MMA(0, 0, At, B0); PG8_MMA(0, 1, At, B1); PG8_BAR; PG8_SCHED;
;             PG8_LDA(At, 1, 1); PG8_STAGE(PG8_SB(1, 0), b3, voffB); PG8_STAGE(PG8_SB(1, 1), b3 + hstep, voffB); PG8_STAGE(PG8_SA(1, 0), a3, voffA);
;             PG8_WAIT_V(8); PG8_WAIT_L(0); PG8_BAR; PG8_MMA(1, 0, At, B0); PG8_MMA(1, 1, At, B1); PG8_BAR; PG8_SCHED;
.Lthird_wait_relaxed_6:
	s_waitcnt lgkmcnt(0)
	s_barrier
	s_setprio 1
	s_waitcnt lgkmcnt(0)
	v_mfma_f32_16x16x32_bf16 v[126:129], v[130:133], v[162:165], v[126:129]
	v_mfma_f32_16x16x32_bf16 v[122:125], v[138:141], v[162:165], v[122:125]
	v_mfma_f32_16x16x32_bf16 v[118:121], v[130:133], v[170:173], v[118:121]
	v_mfma_f32_16x16x32_bf16 v[114:117], v[138:141], v[170:173], v[114:117]
	v_mfma_f32_16x16x32_bf16 v[94:97], v[130:133], v[178:181], v[94:97]
	v_mfma_f32_16x16x32_bf16 v[90:93], v[138:141], v[178:181], v[90:93]
	v_mfma_f32_16x16x32_bf16 v[86:89], v[130:133], v[186:189], v[86:89]
	v_mfma_f32_16x16x32_bf16 v[82:85], v[138:141], v[186:189], v[82:85]
	v_mfma_f32_16x16x32_bf16 v[126:129], v[134:137], v[166:169], v[126:129]
	v_mfma_f32_16x16x32_bf16 v[122:125], v[142:145], v[166:169], v[122:125]
	v_mfma_f32_16x16x32_bf16 v[118:121], v[134:137], v[174:177], v[118:121]
	v_mfma_f32_16x16x32_bf16 v[114:117], v[142:145], v[174:177], v[114:117]
	v_mfma_f32_16x16x32_bf16 v[94:97], v[134:137], v[182:185], v[94:97]
	v_mfma_f32_16x16x32_bf16 v[90:93], v[142:145], v[182:185], v[90:93]
	v_mfma_f32_16x16x32_bf16 v[86:89], v[134:137], v[190:193], v[86:89]
	v_mfma_f32_16x16x32_bf16 v[82:85], v[142:145], v[190:193], v[82:85]
	s_setprio 0
	s_setprio 1
	v_mfma_f32_16x16x32_bf16 v[110:113], v[146:149], v[162:165], v[110:113]
	v_mfma_f32_16x16x32_bf16 v[106:109], v[154:157], v[162:165], v[106:109]
	v_mfma_f32_16x16x32_bf16 v[102:105], v[146:149], v[170:173], v[102:105]
	v_mfma_f32_16x16x32_bf16 v[98:101], v[154:157], v[170:173], v[98:101]
	v_mfma_f32_16x16x32_bf16 v[78:81], v[146:149], v[178:181], v[78:81]
	v_mfma_f32_16x16x32_bf16 v[74:77], v[154:157], v[178:181], v[74:77]
	v_mfma_f32_16x16x32_bf16 v[70:73], v[146:149], v[186:189], v[70:73]
	v_mfma_f32_16x16x32_bf16 v[66:69], v[154:157], v[186:189], v[66:69]
	v_mfma_f32_16x16x32_bf16 v[110:113], v[150:153], v[166:169], v[110:113]
	v_mfma_f32_16x16x32_bf16 v[106:109], v[158:161], v[166:169], v[106:109]
	v_mfma_f32_16x16x32_bf16 v[102:105], v[150:153], v[174:177], v[102:105]
	v_mfma_f32_16x16x32_bf16 v[98:101], v[158:161], v[174:177], v[98:101]
	v_mfma_f32_16x16x32_bf16 v[78:81], v[150:153], v[182:185], v[78:81]
	v_mfma_f32_16x16x32_bf16 v[74:77], v[158:161], v[182:185], v[74:77]
	v_mfma_f32_16x16x32_bf16 v[70:73], v[150:153], v[190:193], v[70:73]
	v_mfma_f32_16x16x32_bf16 v[66:69], v[158:161], v[190:193], v[66:69]
	s_setprio 0
	s_barrier
	s_add_i32 s26, s28, s40
	v_lshl_add_u64 v[194:195], v[232:233], 0, s[64:65]
	s_mov_b32 m0, s26
	ds_read_b128 v[162:165], v249 offset:49152
	ds_read_b128 v[166:169], v249 offset:50176
	ds_read_b128 v[170:173], v249 offset:51200
	ds_read_b128 v[174:177], v249 offset:52224
	ds_read_b128 v[178:181], v249 offset:53248
	ds_read_b128 v[182:185], v249 offset:54272
	ds_read_b128 v[186:189], v249 offset:55296
	ds_read_b128 v[190:193], v249 offset:56320
	global_load_lds_dwordx4 v[194:195], off
	s_add_i32 m0, s26, 0x2000
	s_add_u32 s24, s24, 0x40080
	v_lshl_add_u64 v[194:195], v[230:231], 0, s[64:65]
	s_addc_u32 s25, s25, 0
	s_add_i32 s26, s29, s40
	global_load_lds_dwordx4 v[194:195], off
	v_lshl_add_u64 v[194:195], s[24:25], 0, v[212:213]
	s_mov_b32 m0, s26
	s_nop 0
	global_load_lds_dwordx4 v[194:195], off
	v_lshl_add_u64 v[194:195], s[24:25], 0, v[216:217]
	s_add_i32 m0, s26, 0x2000
	s_nop 0
	global_load_lds_dwordx4 v[194:195], off
	v_lshl_add_u64 v[194:195], v[226:227], 0, s[64:65]
	s_mov_b32 m0, s57
	s_nop 0
	global_load_lds_dwordx4 v[194:195], off
	v_lshl_add_u64 v[194:195], v[228:229], 0, s[64:65]
	s_mov_b32 m0, s62
	s_nop 0
	global_load_lds_dwordx4 v[194:195], off
	s_waitcnt vmcnt(8)
	s_waitcnt lgkmcnt(0)
	s_barrier
	s_setprio 1
	s_waitcnt lgkmcnt(0)
	v_mfma_f32_16x16x32_bf16 v[62:65], v[130:133], v[162:165], v[62:65]
	v_mfma_f32_16x16x32_bf16 v[58:61], v[138:141], v[162:165], v[58:61]
	v_mfma_f32_16x16x32_bf16 v[54:57], v[130:133], v[170:173], v[54:57]
	v_mfma_f32_16x16x32_bf16 v[50:53], v[138:141], v[170:173], v[50:53]
	v_mfma_f32_16x16x32_bf16 v[30:33], v[130:133], v[178:181], v[30:33]
	v_mfma_f32_16x16x32_bf16 v[26:29], v[138:141], v[178:181], v[26:29]
	v_mfma_f32_16x16x32_bf16 v[22:25], v[130:133], v[186:189], v[22:25]
	v_mfma_f32_16x16x32_bf16 v[18:21], v[138:141], v[186:189], v[18:21]
	v_mfma_f32_16x16x32_bf16 v[62:65], v[134:137], v[166:169], v[62:65]
	v_mfma_f32_16x16x32_bf16 v[58:61], v[142:145], v[166:169], v[58:61]
	v_mfma_f32_16x16x32_bf16 v[54:57], v[134:137], v[174:177], v[54:57]
	v_mfma_f32_16x16x32_bf16 v[50:53], v[142:145], v[174:177], v[50:53]
	v_mfma_f32_16x16x32_bf16 v[30:33], v[134:137], v[182:185], v[30:33]
	v_mfma_f32_16x16x32_bf16 v[26:29], v[142:145], v[182:185], v[26:29]
	v_mfma_f32_16x16x32_bf16 v[22:25], v[134:137], v[190:193], v[22:25]
	v_mfma_f32_16x16x32_bf16 v[18:21], v[142:145], v[190:193], v[18:21]
	s_setprio 0
	s_setprio 1
	v_mfma_f32_16x16x32_bf16 v[46:49], v[146:149], v[162:165], v[46:49]
	v_mfma_f32_16x16x32_bf16 v[42:45], v[154:157], v[162:165], v[42:45]
	v_mfma_f32_16x16x32_bf16 v[38:41], v[146:149], v[170:173], v[38:41]
	v_mfma_f32_16x16x32_bf16 v[34:37], v[154:157], v[170:173], v[34:37]
	v_mfma_f32_16x16x32_bf16 v[14:17], v[146:149], v[178:181], v[14:17]
	v_mfma_f32_16x16x32_bf16 v[10:13], v[154:157], v[178:181], v[10:13]
	v_mfma_f32_16x16x32_bf16 v[6:9], v[146:149], v[186:189], v[6:9]
	v_mfma_f32_16x16x32_bf16 v[2:5], v[154:157], v[186:189], v[2:5]
	v_mfma_f32_16x16x32_bf16 v[46:49], v[150:153], v[166:169], v[46:49]
	v_mfma_f32_16x16x32_bf16 v[42:45], v[158:161], v[166:169], v[42:45]
	v_mfma_f32_16x16x32_bf16 v[38:41], v[150:153], v[174:177], v[38:41]
	v_mfma_f32_16x16x32_bf16 v[34:37], v[158:161], v[174:177], v[34:37]
	v_mfma_f32_16x16x32_bf16 v[14:17], v[150:153], v[182:185], v[14:17]
	v_mfma_f32_16x16x32_bf16 v[10:13], v[158:161], v[182:185], v[10:13]
	v_mfma_f32_16x16x32_bf16 v[6:9], v[150:153], v[190:193], v[6:9]
	v_mfma_f32_16x16x32_bf16 v[2:5], v[158:161], v[190:193], v[2:5]
	s_setprio 0
	s_add_i32 s76, s76, 2
	s_add_u32 s22, s22, 0x100
	s_addc_u32 s23, s23, 0
	s_cmp_gt_u32 s76, 13
	s_barrier
	s_cbranch_scc1 .LBB0_162

; #define PG8_STAGE(bufoff, gbase, voff) do { _Pragma("unroll") for (int _i = 0; _i < 2; ++_i) \
;         __builtin_amdgcn_global_load_lds((const unsigned*)((const char*)(gbase) + (voff)[_i]), (PG8_LAS unsigned*)(lds + (bufoff) + ldsw + _i * 8192), 16, 0, 0); } while (0)
; #define PG8_LDA(dst, b, h) do { _Pragma("unroll") for (int m = 0; m < 4; ++m) _Pragma("unroll") for (int k = 0; k < 2; ++k) dst[m][k] = *(const PG8_LAS bf16x8*)(lds + PG8_SA(b, h) + aoff + m * 2048 + k * 1024); } while (0)
; #define PG8_MMA(ai, bj, At, Bt) do { __builtin_amdgcn_s_setprio(1); _Pragma("unroll") for (int m = 0; m < 4; ++m) _Pragma("unroll") for (int n = 0; n < 2; ++n) _Pragma("unroll") for (int k = 0; k < 2; ++k) \
;         acc[ai][bj][m][n] = __builtin_amdgcn_mfma_f32_16x16x32_bf16(Bt[n][k], At[m][k], acc[ai][bj][m][n], 0, 0, 0); __builtin_amdgcn_s_setprio(0); } while (0)
; #define PG8_WAIT_V(n) asm volatile("s_waitcnt vmcnt(" #n ")" ::: "memory")
; #define PG8_WAIT_L(n) asm volatile("s_waitcnt lgkmcnt(" #n ")" ::: "memory")
; #define PG8_BAR __builtin_amdgcn_s_barrier()
; #define PG8_SCHED __builtin_amdgcn_sched_barrier(0)
; template <class Epi, class Sched, bool ALIGN_EPI = false, bool SP2 = false>
; __device__ __forceinline__ void gemm_phase(PG8_LAS unsigned char* lds, const Gemm g, const Sched& S, const Epi& E, const int wave_id) {
;     ...
;             PG8_WAIT_V(8); PG8_WAIT_L(0); PG8_BAR; PG8_MMA(0, 0, At, B0); PG8_MMA(0, 1, At, B1); PG8_BAR; PG8_SCHED;
;             PG8_LDA(At, 1, 1); PG8_STAGE(PG8_SB(1, 0), b3, voffB); PG8_STAGE(PG8_SB(1, 1), b3 + hstep, voffB); PG8_STAGE(PG8_SA(1, 0), a3, voffA);
;             PG8_WAIT_V(8); PG8_WAIT_L(0); PG8_BAR; PG8_MMA(1, 0, At, B0); PG8_MMA(1, 1, At, B1); PG8_BAR; PG8_SCHED;
.Lthird_wait_relaxed_5:
	s_waitcnt lgkmcnt(0)
	s_barrier
	s_setprio 1
	s_waitcnt lgkmcnt(0)
	v_mfma_f32_16x16x32_bf16 v[126:129], v[130:133], v[162:165], v[126:129]
	v_mfma_f32_16x16x32_bf16 v[122:125], v[138:141], v[162:165], v[122:125]
	v_mfma_f32_16x16x32_bf16 v[110:113], v[130:133], v[170:173], v[110:113]
	v_mfma_f32_16x16x32_bf16 v[106:109], v[138:141], v[170:173], v[106:109]
	v_mfma_f32_16x16x32_bf16 v[94:97], v[130:133], v[178:181], v[94:97]
	v_mfma_f32_16x16x32_bf16 v[90:93], v[138:141], v[178:181], v[90:93]
	v_mfma_f32_16x16x32_bf16 v[78:81], v[130:133], v[186:189], v[78:81]
	v_mfma_f32_16x16x32_bf16 v[74:77], v[138:141], v[186:189], v[74:77]
	v_mfma_f32_16x16x32_bf16 v[126:129], v[134:137], v[166:169], v[126:129]
	v_mfma_f32_16x16x32_bf16 v[122:125], v[142:145], v[166:169], v[122:125]
	v_mfma_f32_16x16x32_bf16 v[110:113], v[134:137], v[174:177], v[110:113]
	v_mfma_f32_16x16x32_bf16 v[106:109], v[142:145], v[174:177], v[106:109]
	v_mfma_f32_16x16x32_bf16 v[94:97], v[134:137], v[182:185], v[94:97]
	v_mfma_f32_16x16x32_bf16 v[90:93], v[142:145], v[182:185], v[90:93]
	v_mfma_f32_16x16x32_bf16 v[78:81], v[134:137], v[190:193], v[78:81]
	v_mfma_f32_16x16x32_bf16 v[74:77], v[142:145], v[190:193], v[74:77]
	s_setprio 0
	s_setprio 1
	v_mfma_f32_16x16x32_bf16 v[118:121], v[146:149], v[162:165], v[118:121]
	v_mfma_f32_16x16x32_bf16 v[114:117], v[154:157], v[162:165], v[114:117]
	v_mfma_f32_16x16x32_bf16 v[102:105], v[146:149], v[170:173], v[102:105]
	v_mfma_f32_16x16x32_bf16 v[98:101], v[154:157], v[170:173], v[98:101]
	v_mfma_f32_16x16x32_bf16 v[86:89], v[146:149], v[178:181], v[86:89]
	v_mfma_f32_16x16x32_bf16 v[82:85], v[154:157], v[178:181], v[82:85]
	v_mfma_f32_16x16x32_bf16 v[70:73], v[146:149], v[186:189], v[70:73]
	v_mfma_f32_16x16x32_bf16 v[66:69], v[154:157], v[186:189], v[66:69]
	v_mfma_f32_16x16x32_bf16 v[118:121], v[150:153], v[166:169], v[118:121]
	v_mfma_f32_16x16x32_bf16 v[114:117], v[158:161], v[166:169], v[114:117]
	v_mfma_f32_16x16x32_bf16 v[102:105], v[150:153], v[174:177], v[102:105]
	v_mfma_f32_16x16x32_bf16 v[98:101], v[158:161], v[174:177], v[98:101]
	v_mfma_f32_16x16x32_bf16 v[86:89], v[150:153], v[182:185], v[86:89]
	v_mfma_f32_16x16x32_bf16 v[82:85], v[158:161], v[182:185], v[82:85]
	v_mfma_f32_16x16x32_bf16 v[70:73], v[150:153], v[190:193], v[70:73]
	v_mfma_f32_16x16x32_bf16 v[66:69], v[158:161], v[190:193], v[66:69]
	s_setprio 0
	s_barrier
	s_add_i32 s18, s20, s30
	v_lshl_add_u64 v[194:195], v[232:233], 0, s[64:65]
	s_mov_b32 m0, s18
	ds_read_b128 v[162:165], v247 offset:49152
	ds_read_b128 v[166:169], v247 offset:50176
	ds_read_b128 v[170:173], v247 offset:51200
	ds_read_b128 v[174:177], v247 offset:52224
	ds_read_b128 v[178:181], v247 offset:53248
	ds_read_b128 v[182:185], v247 offset:54272
	ds_read_b128 v[186:189], v247 offset:55296
	ds_read_b128 v[190:193], v247 offset:56320
	global_load_lds_dwordx4 v[194:195], off
	s_add_i32 m0, s18, 0x2000
	s_add_u32 s16, s16, 0xb0080
	v_lshl_add_u64 v[194:195], v[230:231], 0, s[64:65]
	s_addc_u32 s17, s17, 0
	s_add_i32 s18, s21, s30
	global_load_lds_dwordx4 v[194:195], off
	v_lshl_add_u64 v[194:195], s[16:17], 0, v[212:213]
	s_mov_b32 m0, s18
	s_nop 0
	global_load_lds_dwordx4 v[194:195], off
	v_lshl_add_u64 v[194:195], s[16:17], 0, v[216:217]
	s_add_i32 m0, s18, 0x2000
	s_nop 0
	global_load_lds_dwordx4 v[194:195], off
	v_lshl_add_u64 v[194:195], v[226:227], 0, s[64:65]
	s_mov_b32 m0, s42
	s_nop 0
	global_load_lds_dwordx4 v[194:195], off
	v_lshl_add_u64 v[194:195], v[228:229], 0, s[64:65]
	s_mov_b32 m0, s43
	s_nop 0
	global_load_lds_dwordx4 v[194:195], off
	s_waitcnt vmcnt(8)
	s_waitcnt lgkmcnt(0)
	s_barrier
	s_setprio 1
	s_waitcnt lgkmcnt(0)
	v_mfma_f32_16x16x32_bf16 v[62:65], v[130:133], v[162:165], v[62:65]
	v_mfma_f32_16x16x32_bf16 v[58:61], v[138:141], v[162:165], v[58:61]
	v_mfma_f32_16x16x32_bf16 v[46:49], v[130:133], v[170:173], v[46:49]
	v_mfma_f32_16x16x32_bf16 v[42:45], v[138:141], v[170:173], v[42:45]
	v_mfma_f32_16x16x32_bf16 v[30:33], v[130:133], v[178:181], v[30:33]
	v_mfma_f32_16x16x32_bf16 v[26:29], v[138:141], v[178:181], v[26:29]
	v_mfma_f32_16x16x32_bf16 v[14:17], v[130:133], v[186:189], v[14:17]
	v_mfma_f32_16x16x32_bf16 v[10:13], v[138:141], v[186:189], v[10:13]
	v_mfma_f32_16x16x32_bf16 v[62:65], v[134:137], v[166:169], v[62:65]
	v_mfma_f32_16x16x32_bf16 v[58:61], v[142:145], v[166:169], v[58:61]
	v_mfma_f32_16x16x32_bf16 v[46:49], v[134:137], v[174:177], v[46:49]
	v_mfma_f32_16x16x32_bf16 v[42:45], v[142:145], v[174:177], v[42:45]
	v_mfma_f32_16x16x32_bf16 v[30:33], v[134:137], v[182:185], v[30:33]
	v_mfma_f32_16x16x32_bf16 v[26:29], v[142:145], v[182:185], v[26:29]
	v_mfma_f32_16x16x32_bf16 v[14:17], v[134:137], v[190:193], v[14:17]
	v_mfma_f32_16x16x32_bf16 v[10:13], v[142:145], v[190:193], v[10:13]
	s_setprio 0
	s_setprio 1
	v_mfma_f32_16x16x32_bf16 v[54:57], v[146:149], v[162:165], v[54:57]
	v_mfma_f32_16x16x32_bf16 v[50:53], v[154:157], v[162:165], v[50:53]
	v_mfma_f32_16x16x32_bf16 v[38:41], v[146:149], v[170:173], v[38:41]
	v_mfma_f32_16x16x32_bf16 v[34:37], v[154:157], v[170:173], v[34:37]
	v_mfma_f32_16x16x32_bf16 v[22:25], v[146:149], v[178:181], v[22:25]
	v_mfma_f32_16x16x32_bf16 v[18:21], v[154:157], v[178:181], v[18:21]
	v_mfma_f32_16x16x32_bf16 v[6:9], v[146:149], v[186:189], v[6:9]
	v_mfma_f32_16x16x32_bf16 v[2:5], v[154:157], v[186:189], v[2:5]
	v_mfma_f32_16x16x32_bf16 v[54:57], v[150:153], v[166:169], v[54:57]
	v_mfma_f32_16x16x32_bf16 v[50:53], v[158:161], v[166:169], v[50:53]
	v_mfma_f32_16x16x32_bf16 v[38:41], v[150:153], v[174:177], v[38:41]
	v_mfma_f32_16x16x32_bf16 v[34:37], v[158:161], v[174:177], v[34:37]
	v_mfma_f32_16x16x32_bf16 v[22:25], v[150:153], v[182:185], v[22:25]
	v_mfma_f32_16x16x32_bf16 v[18:21], v[158:161], v[182:185], v[18:21]
	v_mfma_f32_16x16x32_bf16 v[6:9], v[150:153], v[190:193], v[6:9]
	v_mfma_f32_16x16x32_bf16 v[2:5], v[158:161], v[190:193], v[2:5]
	s_setprio 0
	s_add_i32 s63, s63, 2
	s_add_u32 s14, s14, 0x100
	s_addc_u32 s15, s15, 0
	s_cmp_gt_u32 s63, 41
	s_barrier
	s_cbranch_scc1 .LBB0_240

; #define PG8_STAGE(bufoff, gbase, voff) do { _Pragma("unroll") for (int _i = 0; _i < 2; ++_i) \
;         __builtin_amdgcn_global_load_lds((const unsigned*)((const char*)(gbase) + (voff)[_i]), (PG8_LAS unsigned*)(lds + (bufoff) + ldsw + _i * 8192), 16, 0, 0); } while (0)
; #define PG8_LDA(dst, b, h) do { _Pragma("unroll") for (int m = 0; m < 4; ++m) _Pragma("unroll") for (int k = 0; k < 2; ++k) dst[m][k] = *(const PG8_LAS bf16x8*)(lds + PG8_SA(b, h) + aoff + m * 2048 + k * 1024); } while (0)
; #define PG8_MMA(ai, bj, At, Bt) do { __builtin_amdgcn_s_setprio(1); _Pragma("unroll") for (int m = 0; m < 4; ++m) _Pragma("unroll") for (int n = 0; n < 2; ++n) _Pragma("unroll") for (int k = 0; k < 2; ++k) \
;         acc[ai][bj][m][n] = __builtin_amdgcn_mfma_f32_16x16x32_bf16(Bt[n][k], At[m][k], acc[ai][bj][m][n], 0, 0, 0); __builtin_amdgcn_s_setprio(0); } while (0)
; #define PG8_WAIT_V(n) asm volatile("s_waitcnt vmcnt(" #n ")" ::: "memory")
; #define PG8_WAIT_L(n) asm volatile("s_waitcnt lgkmcnt(" #n ")" ::: "memory")
; #define PG8_BAR __builtin_amdgcn_s_barrier()
; #define PG8_SCHED __builtin_amdgcn_sched_barrier(0)
; template <class Epi, class Sched, bool ALIGN_EPI = false, bool SP2 = false>
; __device__ __forceinline__ void gemm_phase(PG8_LAS unsigned char* lds, const Gemm g, const Sched& S, const Epi& E, const int wave_id) {
;     ...
;             PG8_WAIT_V(8); PG8_WAIT_L(0); PG8_BAR; PG8_MMA(0, 0, At, B0); PG8_MMA(0, 1, At, B1); PG8_BAR; PG8_SCHED;
;             PG8_LDA(At, 1, 1); PG8_STAGE(PG8_SB(1, 0), b3, voffB); PG8_STAGE(PG8_SB(1, 1), b3 + hstep, voffB); PG8_STAGE(PG8_SA(1, 0), a3, voffA);
;             PG8_WAIT_V(8); PG8_WAIT_L(0); PG8_BAR; PG8_MMA(1, 0, At, B0); PG8_MMA(1, 1, At, B1); PG8_BAR; PG8_SCHED;
.Lthird_wait_relaxed_4:
	s_waitcnt lgkmcnt(0)
	s_barrier
	s_setprio 1
	s_waitcnt lgkmcnt(0)
	v_mfma_f32_16x16x32_bf16 v[126:129], v[130:133], v[162:165], v[126:129]
	v_mfma_f32_16x16x32_bf16 v[122:125], v[138:141], v[162:165], v[122:125]
	v_mfma_f32_16x16x32_bf16 v[110:113], v[130:133], v[170:173], v[110:113]
	v_mfma_f32_16x16x32_bf16 v[106:109], v[138:141], v[170:173], v[106:109]
	v_mfma_f32_16x16x32_bf16 v[94:97], v[130:133], v[178:181], v[94:97]
	v_mfma_f32_16x16x32_bf16 v[90:93], v[138:141], v[178:181], v[90:93]
	v_mfma_f32_16x16x32_bf16 v[78:81], v[130:133], v[186:189], v[78:81]
	v_mfma_f32_16x16x32_bf16 v[74:77], v[138:141], v[186:189], v[74:77]
	v_mfma_f32_16x16x32_bf16 v[126:129], v[134:137], v[166:169], v[126:129]
	v_mfma_f32_16x16x32_bf16 v[122:125], v[142:145], v[166:169], v[122:125]
	v_mfma_f32_16x16x32_bf16 v[110:113], v[134:137], v[174:177], v[110:113]
	v_mfma_f32_16x16x32_bf16 v[106:109], v[142:145], v[174:177], v[106:109]
	v_mfma_f32_16x16x32_bf16 v[94:97], v[134:137], v[182:185], v[94:97]
	v_mfma_f32_16x16x32_bf16 v[90:93], v[142:145], v[182:185], v[90:93]
	v_mfma_f32_16x16x32_bf16 v[78:81], v[134:137], v[190:193], v[78:81]
	v_mfma_f32_16x16x32_bf16 v[74:77], v[142:145], v[190:193], v[74:77]
	s_setprio 0
	s_setprio 1
	v_mfma_f32_16x16x32_bf16 v[118:121], v[146:149], v[162:165], v[118:121]
	v_mfma_f32_16x16x32_bf16 v[114:117], v[154:157], v[162:165], v[114:117]
	v_mfma_f32_16x16x32_bf16 v[102:105], v[146:149], v[170:173], v[102:105]
	v_mfma_f32_16x16x32_bf16 v[98:101], v[154:157], v[170:173], v[98:101]
	v_mfma_f32_16x16x32_bf16 v[86:89], v[146:149], v[178:181], v[86:89]
	v_mfma_f32_16x16x32_bf16 v[82:85], v[154:157], v[178:181], v[82:85]
	v_mfma_f32_16x16x32_bf16 v[70:73], v[146:149], v[186:189], v[70:73]
	v_mfma_f32_16x16x32_bf16 v[66:69], v[154:157], v[186:189], v[66:69]
	v_mfma_f32_16x16x32_bf16 v[118:121], v[150:153], v[166:169], v[118:121]
	v_mfma_f32_16x16x32_bf16 v[114:117], v[158:161], v[166:169], v[114:117]
	v_mfma_f32_16x16x32_bf16 v[102:105], v[150:153], v[174:177], v[102:105]
	v_mfma_f32_16x16x32_bf16 v[98:101], v[158:161], v[174:177], v[98:101]
	v_mfma_f32_16x16x32_bf16 v[86:89], v[150:153], v[182:185], v[86:89]
	v_mfma_f32_16x16x32_bf16 v[82:85], v[158:161], v[182:185], v[82:85]
	v_mfma_f32_16x16x32_bf16 v[70:73], v[150:153], v[190:193], v[70:73]
	v_mfma_f32_16x16x32_bf16 v[66:69], v[158:161], v[190:193], v[66:69]
	s_setprio 0
	s_barrier
	s_add_i32 s14, s34, s90
	v_lshl_add_u64 v[194:195], v[232:233], 0, s[64:65]
	s_mov_b32 m0, s14
	ds_read_b128 v[162:165], v247 offset:49152
	ds_read_b128 v[166:169], v247 offset:50176
	ds_read_b128 v[170:173], v247 offset:51200
	ds_read_b128 v[174:177], v247 offset:52224
	ds_read_b128 v[178:181], v247 offset:53248
	ds_read_b128 v[182:185], v247 offset:54272
	ds_read_b128 v[186:189], v247 offset:55296
	ds_read_b128 v[190:193], v247 offset:56320
	global_load_lds_dwordx4 v[194:195], off
	s_add_i32 m0, s14, 0x2000
	s_add_u32 s12, s12, 0x40080
	v_lshl_add_u64 v[194:195], v[230:231], 0, s[64:65]
	s_addc_u32 s13, s13, 0
	s_add_i32 s14, s35, s90
	global_load_lds_dwordx4 v[194:195], off
	v_lshl_add_u64 v[194:195], s[12:13], 0, v[212:213]
	s_mov_b32 m0, s14
	s_nop 0
	global_load_lds_dwordx4 v[194:195], off
	v_lshl_add_u64 v[194:195], s[12:13], 0, v[216:217]
	s_add_i32 m0, s14, 0x2000
	s_nop 0
	global_load_lds_dwordx4 v[194:195], off
	v_lshl_add_u64 v[194:195], v[226:227], 0, s[64:65]
	s_mov_b32 m0, s63
	s_nop 0
	global_load_lds_dwordx4 v[194:195], off
	v_lshl_add_u64 v[194:195], v[228:229], 0, s[64:65]
	s_mov_b32 m0, s68
	s_nop 0
	global_load_lds_dwordx4 v[194:195], off
	s_waitcnt vmcnt(8)
	s_waitcnt lgkmcnt(0)
	s_barrier
	s_setprio 1
	s_waitcnt lgkmcnt(0)
	v_mfma_f32_16x16x32_bf16 v[62:65], v[130:133], v[162:165], v[62:65]
	v_mfma_f32_16x16x32_bf16 v[58:61], v[138:141], v[162:165], v[58:61]
	v_mfma_f32_16x16x32_bf16 v[46:49], v[130:133], v[170:173], v[46:49]
	v_mfma_f32_16x16x32_bf16 v[42:45], v[138:141], v[170:173], v[42:45]
	v_mfma_f32_16x16x32_bf16 v[30:33], v[130:133], v[178:181], v[30:33]
	v_mfma_f32_16x16x32_bf16 v[26:29], v[138:141], v[178:181], v[26:29]
	v_mfma_f32_16x16x32_bf16 v[14:17], v[130:133], v[186:189], v[14:17]
	v_mfma_f32_16x16x32_bf16 v[10:13], v[138:141], v[186:189], v[10:13]
	v_mfma_f32_16x16x32_bf16 v[62:65], v[134:137], v[166:169], v[62:65]
	v_mfma_f32_16x16x32_bf16 v[58:61], v[142:145], v[166:169], v[58:61]
	v_mfma_f32_16x16x32_bf16 v[46:49], v[134:137], v[174:177], v[46:49]
	v_mfma_f32_16x16x32_bf16 v[42:45], v[142:145], v[174:177], v[42:45]
	v_mfma_f32_16x16x32_bf16 v[30:33], v[134:137], v[182:185], v[30:33]
	v_mfma_f32_16x16x32_bf16 v[26:29], v[142:145], v[182:185], v[26:29]
	v_mfma_f32_16x16x32_bf16 v[14:17], v[134:137], v[190:193], v[14:17]
	v_mfma_f32_16x16x32_bf16 v[10:13], v[142:145], v[190:193], v[10:13]
	s_setprio 0
	s_setprio 1
	v_mfma_f32_16x16x32_bf16 v[54:57], v[146:149], v[162:165], v[54:57]
	v_mfma_f32_16x16x32_bf16 v[50:53], v[154:157], v[162:165], v[50:53]
	v_mfma_f32_16x16x32_bf16 v[38:41], v[146:149], v[170:173], v[38:41]
	v_mfma_f32_16x16x32_bf16 v[34:37], v[154:157], v[170:173], v[34:37]
	v_mfma_f32_16x16x32_bf16 v[22:25], v[146:149], v[178:181], v[22:25]
	v_mfma_f32_16x16x32_bf16 v[18:21], v[154:157], v[178:181], v[18:21]
	v_mfma_f32_16x16x32_bf16 v[6:9], v[146:149], v[186:189], v[6:9]
	v_mfma_f32_16x16x32_bf16 v[2:5], v[154:157], v[186:189], v[2:5]
	v_mfma_f32_16x16x32_bf16 v[54:57], v[150:153], v[166:169], v[54:57]
	v_mfma_f32_16x16x32_bf16 v[50:53], v[158:161], v[166:169], v[50:53]
	v_mfma_f32_16x16x32_bf16 v[38:41], v[150:153], v[174:177], v[38:41]
	v_mfma_f32_16x16x32_bf16 v[34:37], v[158:161], v[174:177], v[34:37]
	v_mfma_f32_16x16x32_bf16 v[22:25], v[150:153], v[182:185], v[22:25]
	v_mfma_f32_16x16x32_bf16 v[18:21], v[158:161], v[182:185], v[18:21]
	v_mfma_f32_16x16x32_bf16 v[6:9], v[150:153], v[190:193], v[6:9]
	v_mfma_f32_16x16x32_bf16 v[2:5], v[158:161], v[190:193], v[2:5]
	s_setprio 0
	s_add_i32 s40, s40, 2
	s_add_u32 s10, s10, 0x100
	s_addc_u32 s11, s11, 0
	s_cmp_gt_u32 s40, 13
	s_barrier
	s_cbranch_scc1 .LBB0_425

; #define PG8_STAGE(bufoff, gbase, voff) do { _Pragma("unroll") for (int _i = 0; _i < 2; ++_i) \
;         __builtin_amdgcn_global_load_lds((const unsigned*)((const char*)(gbase) + (voff)[_i]), (PG8_LAS unsigned*)(lds + (bufoff) + ldsw + _i * 8192), 16, 0, 0); } while (0)
; #define PG8_LDA(dst, b, h) do { _Pragma("unroll") for (int m = 0; m < 4; ++m) _Pragma("unroll") for (int k = 0; k < 2; ++k) dst[m][k] = *(const PG8_LAS bf16x8*)(lds + PG8_SA(b, h) + aoff + m * 2048 + k * 1024); } while (0)
; #define PG8_MMA(ai, bj, At, Bt) do { __builtin_amdgcn_s_setprio(1); _Pragma("unroll") for (int m = 0; m < 4; ++m) _Pragma("unroll") for (int n = 0; n < 2; ++n) _Pragma("unroll") for (int k = 0; k < 2; ++k) \
;         acc[ai][bj][m][n] = __builtin_amdgcn_mfma_f32_16x16x32_bf16(Bt[n][k], At[m][k], acc[ai][bj][m][n], 0, 0, 0); __builtin_amdgcn_s_setprio(0); } while (0)
; #define PG8_WAIT_V(n) asm volatile("s_waitcnt vmcnt(" #n ")" ::: "memory")
; #define PG8_WAIT_L(n) asm volatile("s_waitcnt lgkmcnt(" #n ")" ::: "memory")
; #define PG8_BAR __builtin_amdgcn_s_barrier()
; #define PG8_SCHED __builtin_amdgcn_sched_barrier(0)
; template <class Epi, class Sched, bool ALIGN_EPI = false, bool SP2 = false>
; __device__ __forceinline__ void gemm_phase(PG8_LAS unsigned char* lds, const Gemm g, const Sched& S, const Epi& E, const int wave_id) {
;     ...
;             PG8_WAIT_V(8); PG8_WAIT_L(0); PG8_BAR; PG8_MMA(0, 0, At, B0); PG8_MMA(0, 1, At, B1); PG8_BAR; PG8_SCHED;
;             PG8_LDA(At, 1, 1); PG8_STAGE(PG8_SB(1, 0), b3, voffB); PG8_STAGE(PG8_SB(1, 1), b3 + hstep, voffB); PG8_STAGE(PG8_SA(1, 0), a3, voffA);
;             PG8_WAIT_V(8); PG8_WAIT_L(0); PG8_BAR; PG8_MMA(1, 0, At, B0); PG8_MMA(1, 1, At, B1); PG8_BAR; PG8_SCHED;
.Lthird_wait_relaxed_3:
	s_waitcnt lgkmcnt(0)
	s_barrier
	s_setprio 1
	s_waitcnt lgkmcnt(0)
	v_mfma_f32_16x16x32_bf16 v[126:129], v[130:133], v[162:165], v[126:129]
	v_mfma_f32_16x16x32_bf16 v[122:125], v[138:141], v[162:165], v[122:125]
	v_mfma_f32_16x16x32_bf16 v[110:113], v[130:133], v[170:173], v[110:113]
	v_mfma_f32_16x16x32_bf16 v[106:109], v[138:141], v[170:173], v[106:109]
	v_mfma_f32_16x16x32_bf16 v[94:97], v[130:133], v[178:181], v[94:97]
	v_mfma_f32_16x16x32_bf16 v[90:93], v[138:141], v[178:181], v[90:93]
	v_mfma_f32_16x16x32_bf16 v[78:81], v[130:133], v[186:189], v[78:81]
	v_mfma_f32_16x16x32_bf16 v[74:77], v[138:141], v[186:189], v[74:77]
	v_mfma_f32_16x16x32_bf16 v[126:129], v[134:137], v[166:169], v[126:129]
	v_mfma_f32_16x16x32_bf16 v[122:125], v[142:145], v[166:169], v[122:125]
	v_mfma_f32_16x16x32_bf16 v[110:113], v[134:137], v[174:177], v[110:113]
	v_mfma_f32_16x16x32_bf16 v[106:109], v[142:145], v[174:177], v[106:109]
	v_mfma_f32_16x16x32_bf16 v[94:97], v[134:137], v[182:185], v[94:97]
	v_mfma_f32_16x16x32_bf16 v[90:93], v[142:145], v[182:185], v[90:93]
	v_mfma_f32_16x16x32_bf16 v[78:81], v[134:137], v[190:193], v[78:81]
	v_mfma_f32_16x16x32_bf16 v[74:77], v[142:145], v[190:193], v[74:77]
	s_setprio 0
	s_setprio 1
	v_mfma_f32_16x16x32_bf16 v[118:121], v[146:149], v[162:165], v[118:121]
	v_mfma_f32_16x16x32_bf16 v[114:117], v[154:157], v[162:165], v[114:117]
	v_mfma_f32_16x16x32_bf16 v[102:105], v[146:149], v[170:173], v[102:105]
	v_mfma_f32_16x16x32_bf16 v[98:101], v[154:157], v[170:173], v[98:101]
	v_mfma_f32_16x16x32_bf16 v[86:89], v[146:149], v[178:181], v[86:89]
	v_mfma_f32_16x16x32_bf16 v[82:85], v[154:157], v[178:181], v[82:85]
	v_mfma_f32_16x16x32_bf16 v[70:73], v[146:149], v[186:189], v[70:73]
	v_mfma_f32_16x16x32_bf16 v[66:69], v[154:157], v[186:189], v[66:69]
	v_mfma_f32_16x16x32_bf16 v[118:121], v[150:153], v[166:169], v[118:121]
	v_mfma_f32_16x16x32_bf16 v[114:117], v[158:161], v[166:169], v[114:117]
	v_mfma_f32_16x16x32_bf16 v[102:105], v[150:153], v[174:177], v[102:105]
	v_mfma_f32_16x16x32_bf16 v[98:101], v[158:161], v[174:177], v[98:101]
	v_mfma_f32_16x16x32_bf16 v[86:89], v[150:153], v[182:185], v[86:89]
	v_mfma_f32_16x16x32_bf16 v[82:85], v[158:161], v[182:185], v[82:85]
	v_mfma_f32_16x16x32_bf16 v[70:73], v[150:153], v[190:193], v[70:73]
	v_mfma_f32_16x16x32_bf16 v[66:69], v[158:161], v[190:193], v[66:69]
	s_setprio 0
	s_barrier
	s_add_i32 s24, s26, s38
	v_lshl_add_u64 v[194:195], v[232:233], 0, s[64:65]
	s_mov_b32 m0, s24
	ds_read_b128 v[162:165], v247 offset:49152
	ds_read_b128 v[166:169], v247 offset:50176
	ds_read_b128 v[170:173], v247 offset:51200
	ds_read_b128 v[174:177], v247 offset:52224
	ds_read_b128 v[178:181], v247 offset:53248
	ds_read_b128 v[182:185], v247 offset:54272
	ds_read_b128 v[186:189], v247 offset:55296
	ds_read_b128 v[190:193], v247 offset:56320
	global_load_lds_dwordx4 v[194:195], off
	s_add_i32 m0, s24, 0x2000
	s_add_u32 s22, s22, 0x40080
	v_lshl_add_u64 v[194:195], v[230:231], 0, s[64:65]
	s_addc_u32 s23, s23, 0
	s_add_i32 s24, s27, s38
	global_load_lds_dwordx4 v[194:195], off
	v_lshl_add_u64 v[194:195], s[22:23], 0, v[212:213]
	s_mov_b32 m0, s24
	s_nop 0
	global_load_lds_dwordx4 v[194:195], off
	v_lshl_add_u64 v[194:195], s[22:23], 0, v[216:217]
	s_add_i32 m0, s24, 0x2000
	s_nop 0
	global_load_lds_dwordx4 v[194:195], off
	v_lshl_add_u64 v[194:195], v[226:227], 0, s[64:65]
	s_mov_b32 m0, s54
	s_nop 0
	global_load_lds_dwordx4 v[194:195], off
	v_lshl_add_u64 v[194:195], v[228:229], 0, s[64:65]
	s_mov_b32 m0, s56
	s_nop 0
	global_load_lds_dwordx4 v[194:195], off
	s_waitcnt vmcnt(8)
	s_waitcnt lgkmcnt(0)
	s_barrier
	s_setprio 1
	s_waitcnt lgkmcnt(0)
	v_mfma_f32_16x16x32_bf16 v[62:65], v[130:133], v[162:165], v[62:65]
	v_mfma_f32_16x16x32_bf16 v[58:61], v[138:141], v[162:165], v[58:61]
	v_mfma_f32_16x16x32_bf16 v[46:49], v[130:133], v[170:173], v[46:49]
	v_mfma_f32_16x16x32_bf16 v[42:45], v[138:141], v[170:173], v[42:45]
	v_mfma_f32_16x16x32_bf16 v[30:33], v[130:133], v[178:181], v[30:33]
	v_mfma_f32_16x16x32_bf16 v[26:29], v[138:141], v[178:181], v[26:29]
	v_mfma_f32_16x16x32_bf16 v[14:17], v[130:133], v[186:189], v[14:17]
	v_mfma_f32_16x16x32_bf16 v[10:13], v[138:141], v[186:189], v[10:13]
	v_mfma_f32_16x16x32_bf16 v[62:65], v[134:137], v[166:169], v[62:65]
	v_mfma_f32_16x16x32_bf16 v[58:61], v[142:145], v[166:169], v[58:61]
	v_mfma_f32_16x16x32_bf16 v[46:49], v[134:137], v[174:177], v[46:49]
	v_mfma_f32_16x16x32_bf16 v[42:45], v[142:145], v[174:177], v[42:45]
	v_mfma_f32_16x16x32_bf16 v[30:33], v[134:137], v[182:185], v[30:33]
	v_mfma_f32_16x16x32_bf16 v[26:29], v[142:145], v[182:185], v[26:29]
	v_mfma_f32_16x16x32_bf16 v[14:17], v[134:137], v[190:193], v[14:17]
	v_mfma_f32_16x16x32_bf16 v[10:13], v[142:145], v[190:193], v[10:13]
	s_setprio 0
	s_setprio 1
	v_mfma_f32_16x16x32_bf16 v[54:57], v[146:149], v[162:165], v[54:57]
	v_mfma_f32_16x16x32_bf16 v[50:53], v[154:157], v[162:165], v[50:53]
	v_mfma_f32_16x16x32_bf16 v[38:41], v[146:149], v[170:173], v[38:41]
	v_mfma_f32_16x16x32_bf16 v[34:37], v[154:157], v[170:173], v[34:37]
	v_mfma_f32_16x16x32_bf16 v[22:25], v[146:149], v[178:181], v[22:25]
	v_mfma_f32_16x16x32_bf16 v[18:21], v[154:157], v[178:181], v[18:21]
	v_mfma_f32_16x16x32_bf16 v[6:9], v[146:149], v[186:189], v[6:9]
	v_mfma_f32_16x16x32_bf16 v[2:5], v[154:157], v[186:189], v[2:5]
	v_mfma_f32_16x16x32_bf16 v[54:57], v[150:153], v[166:169], v[54:57]
	v_mfma_f32_16x16x32_bf16 v[50:53], v[158:161], v[166:169], v[50:53]
	v_mfma_f32_16x16x32_bf16 v[38:41], v[150:153], v[174:177], v[38:41]
	v_mfma_f32_16x16x32_bf16 v[34:37], v[158:161], v[174:177], v[34:37]
	v_mfma_f32_16x16x32_bf16 v[22:25], v[150:153], v[182:185], v[22:25]
	v_mfma_f32_16x16x32_bf16 v[18:21], v[158:161], v[182:185], v[18:21]
	v_mfma_f32_16x16x32_bf16 v[6:9], v[150:153], v[190:193], v[6:9]
	v_mfma_f32_16x16x32_bf16 v[2:5], v[158:161], v[190:193], v[2:5]
	s_setprio 0
	s_add_i32 s74, s74, 2
	s_add_u32 s20, s20, 0x100
	s_addc_u32 s21, s21, 0
	s_cmp_gt_u32 s74, 13
	s_barrier
	s_cbranch_scc1 .LBB0_1826

; #define PG8_STAGE(bufoff, gbase, voff) do { _Pragma("unroll") for (int _i = 0; _i < 2; ++_i) \
;         __builtin_amdgcn_global_load_lds((const unsigned*)((const char*)(gbase) + (voff)[_i]), (PG8_LAS unsigned*)(lds + (bufoff) + ldsw + _i * 8192), 16, 0, 0); } while (0)
; #define PG8_LDA(dst, b, h) do { _Pragma("unroll") for (int m = 0; m < 4; ++m) _Pragma("unroll") for (int k = 0; k < 2; ++k) dst[m][k] = *(const PG8_LAS bf16x8*)(lds + PG8_SA(b, h) + aoff + m * 2048 + k * 1024); } while (0)
; #define PG8_MMA(ai, bj, At, Bt) do { __builtin_amdgcn_s_setprio(1); _Pragma("unroll") for (int m = 0; m < 4; ++m) _Pragma("unroll") for (int n = 0; n < 2; ++n) _Pragma("unroll") for (int k = 0; k < 2; ++k) \
;         acc[ai][bj][m][n] = __builtin_amdgcn_mfma_f32_16x16x32_bf16(Bt[n][k], At[m][k], acc[ai][bj][m][n], 0, 0, 0); __builtin_amdgcn_s_setprio(0); } while (0)
; #define PG8_WAIT_V(n) asm volatile("s_waitcnt vmcnt(" #n ")" ::: "memory")
; #define PG8_WAIT_L(n) asm volatile("s_waitcnt lgkmcnt(" #n ")" ::: "memory")
; #define PG8_BAR __builtin_amdgcn_s_barrier()
; #define PG8_SCHED __builtin_amdgcn_sched_barrier(0)
; template <class Epi, class Sched, bool ALIGN_EPI = false, bool SP2 = false>
; __device__ __forceinline__ void gemm_phase(PG8_LAS unsigned char* lds, const Gemm g, const Sched& S, const Epi& E, const int wave_id) {
;     ...
;             PG8_WAIT_V(8); PG8_WAIT_L(0); PG8_BAR; PG8_MMA(0, 0, At, B0); PG8_MMA(0, 1, At, B1); PG8_BAR; PG8_SCHED;
;             PG8_LDA(At, 1, 1); PG8_STAGE(PG8_SB(1, 0), b3, voffB); PG8_STAGE(PG8_SB(1, 1), b3 + hstep, voffB); PG8_STAGE(PG8_SA(1, 0), a3, voffA);
;             PG8_WAIT_V(8); PG8_WAIT_L(0); PG8_BAR; PG8_MMA(1, 0, At, B0); PG8_MMA(1, 1, At, B1); PG8_BAR; PG8_SCHED;
.Lthird_wait_relaxed_2:
	s_waitcnt lgkmcnt(0)
	s_barrier
	s_setprio 1
	s_waitcnt lgkmcnt(0)
	v_mfma_f32_16x16x32_bf16 v[126:129], v[130:133], v[162:165], v[126:129]
	v_mfma_f32_16x16x32_bf16 v[122:125], v[138:141], v[162:165], v[122:125]
	v_mfma_f32_16x16x32_bf16 v[118:121], v[130:133], v[170:173], v[118:121]
	v_mfma_f32_16x16x32_bf16 v[114:117], v[138:141], v[170:173], v[114:117]
	v_mfma_f32_16x16x32_bf16 v[94:97], v[130:133], v[178:181], v[94:97]
	v_mfma_f32_16x16x32_bf16 v[90:93], v[138:141], v[178:181], v[90:93]
	v_mfma_f32_16x16x32_bf16 v[86:89], v[130:133], v[186:189], v[86:89]
	v_mfma_f32_16x16x32_bf16 v[82:85], v[138:141], v[186:189], v[82:85]
	v_mfma_f32_16x16x32_bf16 v[126:129], v[134:137], v[166:169], v[126:129]
	v_mfma_f32_16x16x32_bf16 v[122:125], v[142:145], v[166:169], v[122:125]
	v_mfma_f32_16x16x32_bf16 v[118:121], v[134:137], v[174:177], v[118:121]
	v_mfma_f32_16x16x32_bf16 v[114:117], v[142:145], v[174:177], v[114:117]
	v_mfma_f32_16x16x32_bf16 v[94:97], v[134:137], v[182:185], v[94:97]
	v_mfma_f32_16x16x32_bf16 v[90:93], v[142:145], v[182:185], v[90:93]
	v_mfma_f32_16x16x32_bf16 v[86:89], v[134:137], v[190:193], v[86:89]
	v_mfma_f32_16x16x32_bf16 v[82:85], v[142:145], v[190:193], v[82:85]
	s_setprio 0
	s_setprio 1
	v_mfma_f32_16x16x32_bf16 v[110:113], v[146:149], v[162:165], v[110:113]
	v_mfma_f32_16x16x32_bf16 v[106:109], v[154:157], v[162:165], v[106:109]
	v_mfma_f32_16x16x32_bf16 v[102:105], v[146:149], v[170:173], v[102:105]
	v_mfma_f32_16x16x32_bf16 v[98:101], v[154:157], v[170:173], v[98:101]
	v_mfma_f32_16x16x32_bf16 v[78:81], v[146:149], v[178:181], v[78:81]
	v_mfma_f32_16x16x32_bf16 v[74:77], v[154:157], v[178:181], v[74:77]
	v_mfma_f32_16x16x32_bf16 v[70:73], v[146:149], v[186:189], v[70:73]
	v_mfma_f32_16x16x32_bf16 v[66:69], v[154:157], v[186:189], v[66:69]
	v_mfma_f32_16x16x32_bf16 v[110:113], v[150:153], v[166:169], v[110:113]
	v_mfma_f32_16x16x32_bf16 v[106:109], v[158:161], v[166:169], v[106:109]
	v_mfma_f32_16x16x32_bf16 v[102:105], v[150:153], v[174:177], v[102:105]
	v_mfma_f32_16x16x32_bf16 v[98:101], v[158:161], v[174:177], v[98:101]
	v_mfma_f32_16x16x32_bf16 v[78:81], v[150:153], v[182:185], v[78:81]
	v_mfma_f32_16x16x32_bf16 v[74:77], v[158:161], v[182:185], v[74:77]
	v_mfma_f32_16x16x32_bf16 v[70:73], v[150:153], v[190:193], v[70:73]
	v_mfma_f32_16x16x32_bf16 v[66:69], v[158:161], v[190:193], v[66:69]
	s_setprio 0
	s_barrier
	s_add_i32 s26, s28, s39
	v_lshl_add_u64 v[194:195], v[232:233], 0, s[64:65]
	s_mov_b32 m0, s26
	ds_read_b128 v[162:165], v247 offset:49152
	ds_read_b128 v[166:169], v247 offset:50176
	ds_read_b128 v[170:173], v247 offset:51200
	ds_read_b128 v[174:177], v247 offset:52224
	ds_read_b128 v[178:181], v247 offset:53248
	ds_read_b128 v[182:185], v247 offset:54272
	ds_read_b128 v[186:189], v247 offset:55296
	ds_read_b128 v[190:193], v247 offset:56320
	global_load_lds_dwordx4 v[194:195], off
	s_add_i32 m0, s26, 0x2000
	s_add_u32 s24, s24, 0x40080
	v_lshl_add_u64 v[194:195], v[230:231], 0, s[64:65]
	s_addc_u32 s25, s25, 0
	s_add_i32 s26, s29, s39
	global_load_lds_dwordx4 v[194:195], off
	v_lshl_add_u64 v[194:195], s[24:25], 0, v[214:215]
	s_mov_b32 m0, s26
	s_nop 0
	global_load_lds_dwordx4 v[194:195], off
	v_lshl_add_u64 v[194:195], s[24:25], 0, v[210:211]
	s_add_i32 m0, s26, 0x2000
	s_nop 0
	global_load_lds_dwordx4 v[194:195], off
	v_lshl_add_u64 v[194:195], v[226:227], 0, s[64:65]
	s_mov_b32 m0, s57
	s_nop 0
	global_load_lds_dwordx4 v[194:195], off
	v_lshl_add_u64 v[194:195], v[228:229], 0, s[64:65]
	s_mov_b32 m0, s62
	s_nop 0
	global_load_lds_dwordx4 v[194:195], off
	s_waitcnt vmcnt(8)
	s_waitcnt lgkmcnt(0)
	s_barrier
	s_setprio 1
	s_waitcnt lgkmcnt(0)
	v_mfma_f32_16x16x32_bf16 v[62:65], v[130:133], v[162:165], v[62:65]
	v_mfma_f32_16x16x32_bf16 v[58:61], v[138:141], v[162:165], v[58:61]
	v_mfma_f32_16x16x32_bf16 v[54:57], v[130:133], v[170:173], v[54:57]
	v_mfma_f32_16x16x32_bf16 v[50:53], v[138:141], v[170:173], v[50:53]
	v_mfma_f32_16x16x32_bf16 v[30:33], v[130:133], v[178:181], v[30:33]
	v_mfma_f32_16x16x32_bf16 v[26:29], v[138:141], v[178:181], v[26:29]
	v_mfma_f32_16x16x32_bf16 v[22:25], v[130:133], v[186:189], v[22:25]
	v_mfma_f32_16x16x32_bf16 v[18:21], v[138:141], v[186:189], v[18:21]
	v_mfma_f32_16x16x32_bf16 v[62:65], v[134:137], v[166:169], v[62:65]
	v_mfma_f32_16x16x32_bf16 v[58:61], v[142:145], v[166:169], v[58:61]
	v_mfma_f32_16x16x32_bf16 v[54:57], v[134:137], v[174:177], v[54:57]
	v_mfma_f32_16x16x32_bf16 v[50:53], v[142:145], v[174:177], v[50:53]
	v_mfma_f32_16x16x32_bf16 v[30:33], v[134:137], v[182:185], v[30:33]
	v_mfma_f32_16x16x32_bf16 v[26:29], v[142:145], v[182:185], v[26:29]
	v_mfma_f32_16x16x32_bf16 v[22:25], v[134:137], v[190:193], v[22:25]
	v_mfma_f32_16x16x32_bf16 v[18:21], v[142:145], v[190:193], v[18:21]
	s_setprio 0
	s_setprio 1
	v_mfma_f32_16x16x32_bf16 v[46:49], v[146:149], v[162:165], v[46:49]
	v_mfma_f32_16x16x32_bf16 v[42:45], v[154:157], v[162:165], v[42:45]
	v_mfma_f32_16x16x32_bf16 v[38:41], v[146:149], v[170:173], v[38:41]
	v_mfma_f32_16x16x32_bf16 v[34:37], v[154:157], v[170:173], v[34:37]
	v_mfma_f32_16x16x32_bf16 v[14:17], v[146:149], v[178:181], v[14:17]
	v_mfma_f32_16x16x32_bf16 v[10:13], v[154:157], v[178:181], v[10:13]
	v_mfma_f32_16x16x32_bf16 v[6:9], v[146:149], v[186:189], v[6:9]
	v_mfma_f32_16x16x32_bf16 v[2:5], v[154:157], v[186:189], v[2:5]
	v_mfma_f32_16x16x32_bf16 v[46:49], v[150:153], v[166:169], v[46:49]
	v_mfma_f32_16x16x32_bf16 v[42:45], v[158:161], v[166:169], v[42:45]
	v_mfma_f32_16x16x32_bf16 v[38:41], v[150:153], v[174:177], v[38:41]
	v_mfma_f32_16x16x32_bf16 v[34:37], v[158:161], v[174:177], v[34:37]
	v_mfma_f32_16x16x32_bf16 v[14:17], v[150:153], v[182:185], v[14:17]
	v_mfma_f32_16x16x32_bf16 v[10:13], v[158:161], v[182:185], v[10:13]
	v_mfma_f32_16x16x32_bf16 v[6:9], v[150:153], v[190:193], v[6:9]
	v_mfma_f32_16x16x32_bf16 v[2:5], v[158:161], v[190:193], v[2:5]
	s_setprio 0
	s_add_i32 s76, s76, 2
	s_add_u32 s22, s22, 0x100
	s_addc_u32 s23, s23, 0
	s_cmp_gt_u32 s76, 13
	s_barrier
	s_cbranch_scc1 .LBB0_1957
